# layer-0 SwiGLU epilogue: row-statistics loads of the 4 row groups per half hoisted and issued together into dead fragment registers (one round trip per half instead of four)
# baseline (speedup 1.0000x reference)
.LBB0_441:
	s_lshl_b32 s23, s36, 8
	s_cmp_eq_u32 s50, 2
	s_cselect_b32 s25, 0x80, 0
	s_or_b32 s23, s23, s25
	v_add_u32_e32 v132, s23, v219
	v_ashrrev_i32_e32 v133, 31, v132
	v_lshlrev_b64 v[2:3], 7, v[132:133]
	v_lshl_add_u64 v[2:3], v[204:205], 0, v[2:3]
	global_load_dwordx4 v[134:137], v[2:3], off
	global_load_dwordx4 v[138:141], v[2:3], off offset:16
	s_mov_b32 s98, 0x800
	s_mov_b32 s99, 0
	v_lshl_add_u64 v[182:183], v[2:3], 0, s[98:99]
	v_lshl_add_u64 v[184:185], v[182:183], 0, s[98:99]
	v_lshl_add_u64 v[186:187], v[184:185], 0, s[98:99]
	global_load_dwordx4 v[150:153], v[182:183], off
	global_load_dwordx4 v[154:157], v[182:183], off offset:16
	global_load_dwordx4 v[158:161], v[184:185], off
	global_load_dwordx4 v[162:165], v[184:185], off offset:16
	global_load_dwordx4 v[166:169], v[186:187], off
	global_load_dwordx4 v[170:173], v[186:187], off offset:16
	v_and_b32_e32 v133, 64, v225
	v_xor_b32_e32 v1, 16, v225
	v_mov_b32_e32 v145, v118
	v_mov_b32_e32 v118, v127
	v_add_u32_e32 v127, 64, v133
	v_cmp_lt_i32_e32 vcc, v1, v127
	v_mov_b32_e32 v144, v126
	v_xor_b32_e32 v148, 32, v225
	v_cndmask_b32_e32 v1, v225, v1, vcc
	v_lshlrev_b32_e32 v126, 2, v1
	v_cmp_lt_i32_e32 vcc, v148, v127
	v_mov_b32_e32 v142, v128
	v_mov_b32_e32 v143, v120
	v_mov_b32_e32 v120, v129
	v_mov_b32_e32 v128, v130
	v_mov_b32_e32 v129, v122
	v_mov_b32_e32 v122, v131
	v_mov_b32_e32 v130, v124
	v_mov_b32_e32 v131, v116
	v_mov_b32_e32 v116, v125
	v_lshl_or_b32 v2, s51, 7, v221
	v_mov_b64_e32 v[124:125], s[14:15]
	v_ashrrev_i32_e32 v3, 31, v2
	v_lshlrev_b64 v[2:3], 1, v[2:3]
	s_waitcnt vmcnt(0)
	v_mov_b32_e32 v146, v134
	v_mov_b32_e32 v147, v138
	v_mov_b32_e32 v138, v135
	v_mov_b32_e32 v134, v136
	v_mov_b32_e32 v135, v140
	v_mov_b32_e32 v140, v137
	v_pk_add_f32 v[136:137], v[146:147], v[138:139]
	v_pk_add_f32 v[134:135], v[134:135], v[140:141]
	s_nop 0
	v_pk_add_f32 v[134:135], v[136:137], v[134:135]
	v_or_b32_e32 v136, 16, v132
	v_add_f32_e32 v1, 0, v134
	v_add_f32_e32 v133, v1, v135
	ds_bpermute_b32 v134, v126, v133
	v_cndmask_b32_e32 v1, v225, v148, vcc
	v_lshlrev_b32_e32 v1, 2, v1
	v_ashrrev_i32_e32 v137, 31, v136
	v_lshlrev_b64 v[138:139], 7, v[136:137]
	s_waitcnt lgkmcnt(0)
	v_add_f32_e32 v127, v133, v134
	ds_bpermute_b32 v133, v1, v127
	v_mad_i64_i32 v[134:135], s[46:47], v132, s72, v[124:125]
	v_lshl_add_u64 v[134:135], v[134:135], 0, v[2:3]
	v_lshl_add_u64 v[138:139], v[204:205], 0, v[138:139]
	s_waitcnt lgkmcnt(0)
	v_add_f32_e32 v127, v127, v133
	v_fmamk_f32 v127, v127, 0x3a000000, v226
	v_rsq_f32_e32 v140, v127
	s_nop 0
	v_pk_mul_f32 v[118:119], v[118:119], v[140:141] op_sel_hi:[1,0]
	v_pk_mul_f32 v[142:143], v[142:143], v[140:141] op_sel_hi:[1,0]
	v_pk_mul_f32 v[120:121], v[120:121], v[140:141] op_sel_hi:[1,0]
	v_pk_mul_f32 v[128:129], v[128:129], v[140:141] op_sel_hi:[1,0]
	v_pk_mul_f32 v[122:123], v[122:123], v[140:141] op_sel_hi:[1,0]
	v_pk_mul_f32 v[130:131], v[130:131], v[140:141] op_sel_hi:[1,0]
	v_pk_mul_f32 v[116:117], v[116:117], v[140:141] op_sel_hi:[1,0]
	v_pk_mul_f32 v[144:145], v[144:145], v[140:141] op_sel_hi:[1,0]
	v_mul_f32_e32 v148, 0xbfb8aa3b, v119
	v_mul_f32_e32 v127, 0xbfb8aa3b, v143
	v_mul_f32_e32 v133, 0xbfb8aa3b, v121
	v_mul_f32_e32 v137, 0xbfb8aa3b, v129
	v_mul_f32_e32 v140, 0xbfb8aa3b, v123
	v_mul_f32_e32 v141, 0xbfb8aa3b, v131
	v_mul_f32_e32 v146, 0xbfb8aa3b, v117
	v_mul_f32_e32 v147, 0xbfb8aa3b, v145
	v_exp_f32_e32 v148, v148
	v_exp_f32_e32 v127, v127
	v_exp_f32_e32 v133, v133
	v_exp_f32_e32 v137, v137
	v_exp_f32_e32 v140, v140
	v_exp_f32_e32 v141, v141
	v_exp_f32_e32 v146, v146
	v_exp_f32_e32 v147, v147
	v_add_f32_e32 v148, 1.0, v148
	v_add_f32_e32 v127, 1.0, v127
	v_add_f32_e32 v133, 1.0, v133
	v_add_f32_e32 v137, 1.0, v137
	v_add_f32_e32 v140, 1.0, v140
	v_add_f32_e32 v141, 1.0, v141
	v_add_f32_e32 v146, 1.0, v146
	v_add_f32_e32 v147, 1.0, v147
	v_rcp_f32_e32 v148, v148
	v_rcp_f32_e32 v127, v127
	v_rcp_f32_e32 v133, v133
	v_rcp_f32_e32 v137, v137
	v_rcp_f32_e32 v140, v140
	v_rcp_f32_e32 v141, v141
	v_rcp_f32_e32 v146, v146
	v_rcp_f32_e32 v147, v147
	v_mul_f32_e32 v119, v119, v148
	v_mul_f32_e32 v127, v143, v127
	v_mul_f32_e32 v121, v121, v133
	v_mul_f32_e32 v129, v129, v137
	v_mul_f32_e32 v123, v123, v140
	v_mul_f32_e32 v131, v131, v141
	v_mul_f32_e32 v117, v117, v146
	v_mul_f32_e32 v133, v145, v147
	v_mul_f32_e32 v119, v118, v119
	v_mul_f32_e32 v127, v142, v127
	v_mul_f32_e32 v120, v120, v121
	v_mul_f32_e32 v121, v128, v129
	v_mul_f32_e32 v122, v122, v123
	v_mul_f32_e32 v123, v130, v131
	v_mul_f32_e32 v128, v116, v117
	v_mul_f32_e32 v129, v144, v133
	v_cvt_pk_bf16_f32 v116, v127, v120
	v_cvt_pk_bf16_f32 v117, v121, v122
	v_cvt_pk_bf16_f32 v118, v123, v128
	v_cvt_pk_bf16_f32 v119, v129, v119
	global_store_dwordx4 v[134:135], v[116:119], off
	v_mov_b32_e32 v129, v104
	v_mov_b32_e32 v104, v113
	v_mov_b32_e32 v113, v106
	v_mov_b32_e32 v106, v115
	v_mov_b32_e32 v115, v100
	v_mov_b32_e32 v128, v112
	v_mov_b32_e32 v112, v114
	v_mov_b32_e32 v114, v108
	v_mov_b32_e32 v108, v110
	v_or_b32_e32 v110, 32, v132
	v_mov_b64_e32 v[116:117], v[150:151]
	v_mov_b64_e32 v[118:119], v[152:153]
	v_mov_b64_e32 v[120:121], v[154:155]
	v_mov_b64_e32 v[122:123], v[156:157]
	v_mov_b32_e32 v130, v116
	v_mov_b32_e32 v131, v120
	v_mov_b32_e32 v120, v117
	v_mov_b32_e32 v116, v118
	v_mov_b32_e32 v117, v122
	v_mov_b32_e32 v122, v119
	v_pk_add_f32 v[118:119], v[130:131], v[120:121]
	v_pk_add_f32 v[116:117], v[116:117], v[122:123]
	s_nop 0
	v_pk_add_f32 v[116:117], v[118:119], v[116:117]
	s_nop 0
	v_add_f32_e32 v100, 0, v116
	v_add_f32_e32 v116, v100, v117
	ds_bpermute_b32 v117, v126, v116
	v_mov_b32_e32 v100, v109
	v_mov_b32_e32 v109, v102
	v_mov_b32_e32 v102, v111
	v_ashrrev_i32_e32 v111, 31, v110
	s_waitcnt lgkmcnt(0)
	v_add_f32_e32 v118, v116, v117
	ds_bpermute_b32 v119, v1, v118
	v_mad_i64_i32 v[116:117], s[46:47], v136, s72, v[124:125]
	v_lshl_add_u64 v[116:117], v[116:117], 0, v[2:3]
	s_waitcnt lgkmcnt(0)
	v_add_f32_e32 v118, v118, v119
	v_fmamk_f32 v118, v118, 0x3a000000, v226
	v_rsq_f32_e32 v120, v118
	v_lshlrev_b64 v[118:119], 7, v[110:111]
	v_lshl_add_u64 v[118:119], v[204:205], 0, v[118:119]
	v_pk_mul_f32 v[102:103], v[102:103], v[120:121] op_sel_hi:[1,0]
	v_pk_mul_f32 v[122:123], v[128:129], v[120:121] op_sel_hi:[1,0]
	v_pk_mul_f32 v[104:105], v[104:105], v[120:121] op_sel_hi:[1,0]
	v_pk_mul_f32 v[112:113], v[112:113], v[120:121] op_sel_hi:[1,0]
	v_pk_mul_f32 v[106:107], v[106:107], v[120:121] op_sel_hi:[1,0]
	v_pk_mul_f32 v[114:115], v[114:115], v[120:121] op_sel_hi:[1,0]
	v_pk_mul_f32 v[100:101], v[100:101], v[120:121] op_sel_hi:[1,0]
	v_pk_mul_f32 v[108:109], v[108:109], v[120:121] op_sel_hi:[1,0]
	v_mul_f32_e32 v131, 0xbfb8aa3b, v103
	v_mul_f32_e32 v111, 0xbfb8aa3b, v123
	v_mul_f32_e32 v120, 0xbfb8aa3b, v105
	v_mul_f32_e32 v121, 0xbfb8aa3b, v113
	v_mul_f32_e32 v127, 0xbfb8aa3b, v107
	v_mul_f32_e32 v128, 0xbfb8aa3b, v115
	v_mul_f32_e32 v129, 0xbfb8aa3b, v101
	v_mul_f32_e32 v130, 0xbfb8aa3b, v109
	v_exp_f32_e32 v131, v131
	v_exp_f32_e32 v111, v111
	v_exp_f32_e32 v120, v120
	v_exp_f32_e32 v121, v121
	v_exp_f32_e32 v127, v127
	v_exp_f32_e32 v128, v128
	v_exp_f32_e32 v129, v129
	v_exp_f32_e32 v130, v130
	v_add_f32_e32 v131, 1.0, v131
	v_add_f32_e32 v111, 1.0, v111
	v_add_f32_e32 v120, 1.0, v120
	v_add_f32_e32 v121, 1.0, v121
	v_add_f32_e32 v127, 1.0, v127
	v_add_f32_e32 v128, 1.0, v128
	v_add_f32_e32 v129, 1.0, v129
	v_add_f32_e32 v130, 1.0, v130
	v_rcp_f32_e32 v131, v131
	v_rcp_f32_e32 v111, v111
	v_rcp_f32_e32 v120, v120
	v_rcp_f32_e32 v121, v121
	v_rcp_f32_e32 v127, v127
	v_rcp_f32_e32 v128, v128
	v_rcp_f32_e32 v129, v129
	v_rcp_f32_e32 v130, v130
	v_mul_f32_e32 v103, v103, v131
	v_mul_f32_e32 v111, v123, v111
	v_mul_f32_e32 v105, v105, v120
	v_mul_f32_e32 v113, v113, v121
	v_mul_f32_e32 v107, v107, v127
	v_mul_f32_e32 v115, v115, v128
	v_mul_f32_e32 v101, v101, v129
	v_mul_f32_e32 v109, v109, v130
	v_mul_f32_e32 v103, v102, v103
	v_mul_f32_e32 v111, v122, v111
	v_mul_f32_e32 v104, v104, v105
	v_mul_f32_e32 v105, v112, v113
	v_mul_f32_e32 v106, v106, v107
	v_mul_f32_e32 v107, v114, v115
	v_mul_f32_e32 v112, v100, v101
	v_mul_f32_e32 v108, v108, v109
	v_cvt_pk_bf16_f32 v100, v111, v104
	v_cvt_pk_bf16_f32 v101, v105, v106
	v_cvt_pk_bf16_f32 v102, v107, v112
	v_cvt_pk_bf16_f32 v103, v108, v103
	global_store_dwordx4 v[116:117], v[100:103], off
	v_mov_b32_e32 v109, v88
	v_mov_b32_e32 v88, v97
	v_mov_b32_e32 v97, v90
	v_mov_b32_e32 v90, v99
	v_mov_b32_e32 v99, v84
	v_mov_b32_e32 v108, v96
	v_mov_b32_e32 v96, v98
	v_mov_b32_e32 v98, v92
	v_mov_b32_e32 v92, v94
	v_or_b32_e32 v94, 48, v132
	v_mov_b64_e32 v[100:101], v[158:159]
	v_mov_b64_e32 v[102:103], v[160:161]
	v_mov_b64_e32 v[104:105], v[162:163]
	v_mov_b64_e32 v[106:107], v[164:165]
	v_mov_b32_e32 v112, v100
	v_mov_b32_e32 v113, v104
	v_mov_b32_e32 v104, v101
	v_mov_b32_e32 v100, v102
	v_mov_b32_e32 v101, v106
	v_mov_b32_e32 v106, v103
	v_pk_add_f32 v[102:103], v[112:113], v[104:105]
	v_pk_add_f32 v[100:101], v[100:101], v[106:107]
	s_nop 0
	v_pk_add_f32 v[100:101], v[102:103], v[100:101]
	s_nop 0
	v_add_f32_e32 v84, 0, v100
	v_add_f32_e32 v100, v84, v101
	ds_bpermute_b32 v101, v126, v100
	v_mov_b32_e32 v84, v93
	v_mov_b32_e32 v93, v86
	v_mov_b32_e32 v86, v95
	v_ashrrev_i32_e32 v95, 31, v94
	s_waitcnt lgkmcnt(0)
	v_add_f32_e32 v102, v100, v101
	ds_bpermute_b32 v103, v1, v102
	v_mad_i64_i32 v[100:101], s[46:47], v110, s72, v[124:125]
	v_lshl_add_u64 v[100:101], v[100:101], 0, v[2:3]
	s_waitcnt lgkmcnt(0)
	v_add_f32_e32 v102, v102, v103
	v_fmamk_f32 v102, v102, 0x3a000000, v226
	v_rsq_f32_e32 v104, v102
	v_lshlrev_b64 v[102:103], 7, v[94:95]
	v_lshl_add_u64 v[102:103], v[204:205], 0, v[102:103]
	v_pk_mul_f32 v[86:87], v[86:87], v[104:105] op_sel_hi:[1,0]
	v_pk_mul_f32 v[106:107], v[108:109], v[104:105] op_sel_hi:[1,0]
	v_pk_mul_f32 v[88:89], v[88:89], v[104:105] op_sel_hi:[1,0]
	v_pk_mul_f32 v[96:97], v[96:97], v[104:105] op_sel_hi:[1,0]
	v_pk_mul_f32 v[90:91], v[90:91], v[104:105] op_sel_hi:[1,0]
	v_pk_mul_f32 v[98:99], v[98:99], v[104:105] op_sel_hi:[1,0]
	v_pk_mul_f32 v[84:85], v[84:85], v[104:105] op_sel_hi:[1,0]
	v_pk_mul_f32 v[92:93], v[92:93], v[104:105] op_sel_hi:[1,0]
	v_mul_f32_e32 v112, 0xbfb8aa3b, v87
	v_mul_f32_e32 v95, 0xbfb8aa3b, v107
	v_mul_f32_e32 v104, 0xbfb8aa3b, v89
	v_mul_f32_e32 v105, 0xbfb8aa3b, v97
	v_mul_f32_e32 v108, 0xbfb8aa3b, v91
	v_mul_f32_e32 v109, 0xbfb8aa3b, v99
	v_mul_f32_e32 v110, 0xbfb8aa3b, v85
	v_mul_f32_e32 v111, 0xbfb8aa3b, v93
	v_exp_f32_e32 v112, v112
	v_exp_f32_e32 v95, v95
	v_exp_f32_e32 v104, v104
	v_exp_f32_e32 v105, v105
	v_exp_f32_e32 v108, v108
	v_exp_f32_e32 v109, v109
	v_exp_f32_e32 v110, v110
	v_exp_f32_e32 v111, v111
	v_add_f32_e32 v112, 1.0, v112
	v_add_f32_e32 v95, 1.0, v95
	v_add_f32_e32 v104, 1.0, v104
	v_add_f32_e32 v105, 1.0, v105
	v_add_f32_e32 v108, 1.0, v108
	v_add_f32_e32 v109, 1.0, v109
	v_add_f32_e32 v110, 1.0, v110
	v_add_f32_e32 v111, 1.0, v111
	v_rcp_f32_e32 v112, v112
	v_rcp_f32_e32 v95, v95
	v_rcp_f32_e32 v104, v104
	v_rcp_f32_e32 v105, v105
	v_rcp_f32_e32 v108, v108
	v_rcp_f32_e32 v109, v109
	v_rcp_f32_e32 v110, v110
	v_rcp_f32_e32 v111, v111
	v_mul_f32_e32 v87, v87, v112
	v_mul_f32_e32 v95, v107, v95
	v_mul_f32_e32 v89, v89, v104
	v_mul_f32_e32 v97, v97, v105
	v_mul_f32_e32 v91, v91, v108
	v_mul_f32_e32 v99, v99, v109
	v_mul_f32_e32 v85, v85, v110
	v_mul_f32_e32 v93, v93, v111
	v_mul_f32_e32 v87, v86, v87
	v_mul_f32_e32 v95, v106, v95
	v_mul_f32_e32 v88, v88, v89
	v_mul_f32_e32 v89, v96, v97
	v_mul_f32_e32 v90, v90, v91
	v_mul_f32_e32 v91, v98, v99
	v_mul_f32_e32 v96, v84, v85
	v_mul_f32_e32 v92, v92, v93
	v_cvt_pk_bf16_f32 v84, v95, v88
	v_cvt_pk_bf16_f32 v85, v89, v90
	v_cvt_pk_bf16_f32 v86, v91, v96
	v_cvt_pk_bf16_f32 v87, v92, v87
	global_store_dwordx4 v[100:101], v[84:87], off
	v_mov_b32_e32 v93, v76
	v_mov_b32_e32 v76, v81
	v_mov_b32_e32 v92, v80
	v_mov_b32_e32 v80, v82
	v_mov_b32_e32 v82, v68
	v_mov_b32_e32 v68, v70
	v_mov_b64_e32 v[84:85], v[166:167]
	v_mov_b64_e32 v[86:87], v[168:169]
	v_mov_b64_e32 v[88:89], v[170:171]
	v_mov_b64_e32 v[90:91], v[172:173]
	v_mov_b32_e32 v96, v84
	v_mov_b32_e32 v97, v88
	v_mov_b32_e32 v88, v85
	v_mov_b32_e32 v84, v86
	v_mov_b32_e32 v85, v90
	v_mov_b32_e32 v90, v87
	v_pk_add_f32 v[86:87], v[96:97], v[88:89]
	v_pk_add_f32 v[84:85], v[84:85], v[90:91]
	s_nop 0
	v_pk_add_f32 v[84:85], v[86:87], v[84:85]
	s_nop 0
	v_add_f32_e32 v81, 0, v84
	v_add_f32_e32 v84, v81, v85
	ds_bpermute_b32 v85, v126, v84
	v_mov_b32_e32 v81, v78
	v_mov_b32_e32 v78, v83
	v_mov_b32_e32 v83, v72
	v_mov_b32_e32 v72, v69
	s_waitcnt lgkmcnt(0)
	v_add_f32_e32 v84, v84, v85
	ds_bpermute_b32 v85, v1, v84
	v_mov_b32_e32 v69, v74
	v_mov_b32_e32 v74, v71
	s_waitcnt lgkmcnt(0)
	v_add_f32_e32 v70, v84, v85
	v_fmamk_f32 v70, v70, 0x3a000000, v226
	v_mul_f32_e32 v71, 0x4b800000, v70
	v_cmp_gt_f32_e32 vcc, s71, v70
	s_nop 1
	v_cndmask_b32_e32 v70, v70, v71, vcc
	v_rsq_f32_e32 v86, v70
	v_mad_i64_i32 v[70:71], s[46:47], v94, s72, v[124:125]
	v_lshl_add_u64 v[84:85], v[70:71], 0, v[2:3]
	v_mul_f32_e32 v70, 0x45800000, v86
	v_cndmask_b32_e32 v70, v86, v70, vcc
	v_pk_mul_f32 v[86:87], v[92:93], v[70:71] op_sel_hi:[1,0]
	v_pk_mul_f32 v[76:77], v[76:77], v[70:71] op_sel_hi:[1,0]
	v_pk_mul_f32 v[80:81], v[80:81], v[70:71] op_sel_hi:[1,0]
	v_pk_mul_f32 v[78:79], v[78:79], v[70:71] op_sel_hi:[1,0]
	v_pk_mul_f32 v[82:83], v[82:83], v[70:71] op_sel_hi:[1,0]
	v_pk_mul_f32 v[72:73], v[72:73], v[70:71] op_sel_hi:[1,0]
	v_pk_mul_f32 v[68:69], v[68:69], v[70:71] op_sel_hi:[1,0]
	v_pk_mul_f32 v[70:71], v[74:75], v[70:71] op_sel_hi:[1,0]
	v_mul_f32_e32 v74, 0xbfb8aa3b, v87
	v_mul_f32_e32 v93, 0xbfb8aa3b, v71
	v_mul_f32_e32 v75, 0xbfb8aa3b, v77
	v_mul_f32_e32 v88, 0xbfb8aa3b, v81
	v_mul_f32_e32 v89, 0xbfb8aa3b, v79
	v_mul_f32_e32 v90, 0xbfb8aa3b, v83
	v_mul_f32_e32 v91, 0xbfb8aa3b, v73
	v_mul_f32_e32 v92, 0xbfb8aa3b, v69
	v_exp_f32_e32 v93, v93
	v_exp_f32_e32 v74, v74
	v_exp_f32_e32 v75, v75
	v_exp_f32_e32 v88, v88
	v_exp_f32_e32 v89, v89
	v_exp_f32_e32 v90, v90
	v_exp_f32_e32 v91, v91
	v_exp_f32_e32 v92, v92
	v_add_f32_e32 v93, 1.0, v93
	v_add_f32_e32 v74, 1.0, v74
	v_add_f32_e32 v75, 1.0, v75
	v_add_f32_e32 v88, 1.0, v88
	v_add_f32_e32 v89, 1.0, v89
	v_add_f32_e32 v90, 1.0, v90
	v_add_f32_e32 v91, 1.0, v91
	v_add_f32_e32 v92, 1.0, v92
	v_rcp_f32_e32 v93, v93
	v_rcp_f32_e32 v74, v74
	v_rcp_f32_e32 v75, v75
	v_rcp_f32_e32 v88, v88
	v_rcp_f32_e32 v89, v89
	v_rcp_f32_e32 v90, v90
	v_rcp_f32_e32 v91, v91
	v_rcp_f32_e32 v92, v92
	v_mul_f32_e32 v71, v71, v93
	v_mul_f32_e32 v74, v87, v74
	v_mul_f32_e32 v75, v77, v75
	v_mul_f32_e32 v77, v81, v88
	v_mul_f32_e32 v79, v79, v89
	v_mul_f32_e32 v81, v83, v90
	v_mul_f32_e32 v73, v73, v91
	v_mul_f32_e32 v69, v69, v92
	v_mul_f32_e32 v71, v70, v71
	v_mul_f32_e32 v74, v86, v74
	v_mul_f32_e32 v75, v76, v75
	v_mul_f32_e32 v76, v80, v77
	v_mul_f32_e32 v77, v78, v79
	v_mul_f32_e32 v78, v82, v81
	v_mul_f32_e32 v72, v72, v73
	v_mul_f32_e32 v73, v68, v69
	v_cvt_pk_bf16_f32 v68, v74, v75
	v_cvt_pk_bf16_f32 v69, v76, v77
	v_cvt_pk_bf16_f32 v70, v78, v72
	v_cvt_pk_bf16_f32 v71, v73, v71
	global_store_dwordx4 v[84:85], v[68:71], off
	s_and_b64 vcc, exec, s[10:11]
	s_cbranch_vccz .LBB0_443
	s_andn2_b64 vcc, exec, s[26:27]
	s_mov_b64 s[10:11], -1
	s_cbranch_vccnz .LBB0_422
	s_branch .LBB0_444
.LBB0_443:
	v_add_u32_e32 v76, 0x80, v132
	v_ashrrev_i32_e32 v77, 31, v76
	v_lshlrev_b64 v[68:69], 7, v[76:77]
	v_lshl_add_u64 v[72:73], v[204:205], 0, v[68:69]
	s_mov_b32 s98, 0x800
	s_mov_b32 s99, 0
	v_lshl_add_u64 v[182:183], v[72:73], 0, s[98:99]
	v_lshl_add_u64 v[184:185], v[182:183], 0, s[98:99]
	v_lshl_add_u64 v[186:187], v[184:185], 0, s[98:99]
	global_load_dwordx4 v[68:71], v[72:73], off
	s_nop 0
	global_load_dwordx4 v[72:75], v[72:73], off offset:16
	global_load_dwordx4 v[150:153], v[182:183], off
	global_load_dwordx4 v[154:157], v[182:183], off offset:16
	global_load_dwordx4 v[158:161], v[184:185], off
	global_load_dwordx4 v[162:165], v[184:185], off offset:16
	global_load_dwordx4 v[166:169], v[186:187], off
	global_load_dwordx4 v[170:173], v[186:187], off offset:16
	v_mov_b32_e32 v78, v64
	v_mov_b32_e32 v79, v56
	v_mov_b32_e32 v56, v65
	v_mov_b32_e32 v64, v66
	v_mov_b32_e32 v65, v58
	v_mov_b32_e32 v58, v67
	v_mov_b32_e32 v66, v60
	v_mov_b32_e32 v67, v52
	v_mov_b32_e32 v52, v61
	s_waitcnt vmcnt(0)
	v_mov_b32_e32 v60, v68
	s_waitcnt vmcnt(0)
	v_mov_b32_e32 v61, v72
	v_mov_b32_e32 v72, v69
	v_mov_b32_e32 v68, v70
	v_mov_b32_e32 v69, v74
	v_mov_b32_e32 v74, v71
	v_pk_add_f32 v[60:61], v[60:61], v[72:73]
	v_pk_add_f32 v[68:69], v[68:69], v[74:75]
	s_nop 0
	v_pk_add_f32 v[60:61], v[60:61], v[68:69]
	v_mov_b32_e32 v68, v62
	v_add_f32_e32 v60, 0, v60
	v_add_f32_e32 v70, v60, v61
	ds_bpermute_b32 v71, v126, v70
	v_add_u32_e32 v62, 0x90, v132
	v_mov_b32_e32 v69, v54
	v_mov_b32_e32 v54, v63
	v_ashrrev_i32_e32 v63, 31, v62
	s_waitcnt lgkmcnt(0)
	v_add_f32_e32 v72, v70, v71
	ds_bpermute_b32 v73, v1, v72
	v_mov_b64_e32 v[60:61], s[14:15]
	v_mad_i64_i32 v[70:71], s[10:11], v76, s72, v[60:61]
	v_lshl_add_u64 v[70:71], v[70:71], 0, v[2:3]
	s_waitcnt lgkmcnt(0)
	v_add_f32_e32 v72, v72, v73
	v_fmamk_f32 v72, v72, 0x3a000000, v226
	v_rsq_f32_e32 v74, v72
	v_lshlrev_b64 v[72:73], 7, v[62:63]
	v_lshl_add_u64 v[72:73], v[204:205], 0, v[72:73]
	v_pk_mul_f32 v[54:55], v[54:55], v[74:75] op_sel_hi:[1,0]
	v_pk_mul_f32 v[76:77], v[78:79], v[74:75] op_sel_hi:[1,0]
	v_pk_mul_f32 v[56:57], v[56:57], v[74:75] op_sel_hi:[1,0]
	v_pk_mul_f32 v[64:65], v[64:65], v[74:75] op_sel_hi:[1,0]
	v_pk_mul_f32 v[58:59], v[58:59], v[74:75] op_sel_hi:[1,0]
	v_pk_mul_f32 v[66:67], v[66:67], v[74:75] op_sel_hi:[1,0]
	v_pk_mul_f32 v[52:53], v[52:53], v[74:75] op_sel_hi:[1,0]
	v_pk_mul_f32 v[68:69], v[68:69], v[74:75] op_sel_hi:[1,0]
	v_mul_f32_e32 v82, 0xbfb8aa3b, v55
	v_mul_f32_e32 v63, 0xbfb8aa3b, v77
	v_mul_f32_e32 v74, 0xbfb8aa3b, v57
	v_mul_f32_e32 v75, 0xbfb8aa3b, v65
	v_mul_f32_e32 v78, 0xbfb8aa3b, v59
	v_mul_f32_e32 v79, 0xbfb8aa3b, v67
	v_mul_f32_e32 v80, 0xbfb8aa3b, v53
	v_mul_f32_e32 v81, 0xbfb8aa3b, v69
	v_exp_f32_e32 v82, v82
	v_exp_f32_e32 v63, v63
	v_exp_f32_e32 v74, v74
	v_exp_f32_e32 v75, v75
	v_exp_f32_e32 v78, v78
	v_exp_f32_e32 v79, v79
	v_exp_f32_e32 v80, v80
	v_exp_f32_e32 v81, v81
	v_add_f32_e32 v82, 1.0, v82
	v_add_f32_e32 v63, 1.0, v63
	v_add_f32_e32 v74, 1.0, v74
	v_add_f32_e32 v75, 1.0, v75
	v_add_f32_e32 v78, 1.0, v78
	v_add_f32_e32 v79, 1.0, v79
	v_add_f32_e32 v80, 1.0, v80
	v_add_f32_e32 v81, 1.0, v81
	v_rcp_f32_e32 v82, v82
	v_rcp_f32_e32 v63, v63
	v_rcp_f32_e32 v74, v74
	v_rcp_f32_e32 v75, v75
	v_rcp_f32_e32 v78, v78
	v_rcp_f32_e32 v79, v79
	v_rcp_f32_e32 v80, v80
	v_rcp_f32_e32 v81, v81
	v_mul_f32_e32 v55, v55, v82
	v_mul_f32_e32 v63, v77, v63
	v_mul_f32_e32 v57, v57, v74
	v_mul_f32_e32 v65, v65, v75
	v_mul_f32_e32 v59, v59, v78
	v_mul_f32_e32 v67, v67, v79
	v_mul_f32_e32 v53, v53, v80
	v_mul_f32_e32 v69, v69, v81
	v_mul_f32_e32 v55, v54, v55
	v_mul_f32_e32 v63, v76, v63
	v_mul_f32_e32 v56, v56, v57
	v_mul_f32_e32 v57, v64, v65
	v_mul_f32_e32 v58, v58, v59
	v_mul_f32_e32 v59, v66, v67
	v_mul_f32_e32 v64, v52, v53
	v_mul_f32_e32 v65, v68, v69
	v_cvt_pk_bf16_f32 v52, v63, v56
	v_cvt_pk_bf16_f32 v53, v57, v58
	v_cvt_pk_bf16_f32 v54, v59, v64
	v_cvt_pk_bf16_f32 v55, v65, v55
	global_store_dwordx4 v[70:71], v[52:55], off
	v_mov_b32_e32 v65, v40
	v_mov_b32_e32 v40, v49
	v_mov_b32_e32 v49, v42
	v_mov_b32_e32 v42, v51
	v_mov_b32_e32 v51, v36
	v_mov_b32_e32 v64, v48
	v_mov_b32_e32 v48, v50
	v_mov_b32_e32 v50, v44
	v_mov_b32_e32 v44, v46
	v_add_u32_e32 v46, 0xa0, v132
	v_mov_b64_e32 v[52:53], v[150:151]
	v_mov_b64_e32 v[54:55], v[152:153]
	v_mov_b64_e32 v[56:57], v[154:155]
	v_mov_b64_e32 v[58:59], v[156:157]
	v_mov_b32_e32 v66, v52
	v_mov_b32_e32 v67, v56
	v_mov_b32_e32 v56, v53
	v_mov_b32_e32 v52, v54
	v_mov_b32_e32 v53, v58
	v_mov_b32_e32 v58, v55
	v_pk_add_f32 v[54:55], v[66:67], v[56:57]
	v_pk_add_f32 v[52:53], v[52:53], v[58:59]
	s_nop 0
	v_pk_add_f32 v[52:53], v[54:55], v[52:53]
	s_nop 0
	v_add_f32_e32 v36, 0, v52
	v_add_f32_e32 v52, v36, v53
	ds_bpermute_b32 v53, v126, v52
	v_mov_b32_e32 v36, v45
	v_mov_b32_e32 v45, v38
	v_mov_b32_e32 v38, v47
	v_ashrrev_i32_e32 v47, 31, v46
	s_waitcnt lgkmcnt(0)
	v_add_f32_e32 v54, v52, v53
	ds_bpermute_b32 v55, v1, v54
	v_mad_i64_i32 v[52:53], s[10:11], v62, s72, v[60:61]
	v_lshl_add_u64 v[52:53], v[52:53], 0, v[2:3]
	s_waitcnt lgkmcnt(0)
	v_add_f32_e32 v54, v54, v55
	v_fmamk_f32 v54, v54, 0x3a000000, v226
	v_rsq_f32_e32 v56, v54
	v_lshlrev_b64 v[54:55], 7, v[46:47]
	v_lshl_add_u64 v[54:55], v[204:205], 0, v[54:55]
	v_pk_mul_f32 v[38:39], v[38:39], v[56:57] op_sel_hi:[1,0]
	v_pk_mul_f32 v[58:59], v[64:65], v[56:57] op_sel_hi:[1,0]
	v_pk_mul_f32 v[40:41], v[40:41], v[56:57] op_sel_hi:[1,0]
	v_pk_mul_f32 v[48:49], v[48:49], v[56:57] op_sel_hi:[1,0]
	v_pk_mul_f32 v[42:43], v[42:43], v[56:57] op_sel_hi:[1,0]
	v_pk_mul_f32 v[50:51], v[50:51], v[56:57] op_sel_hi:[1,0]
	v_pk_mul_f32 v[36:37], v[36:37], v[56:57] op_sel_hi:[1,0]
	v_pk_mul_f32 v[44:45], v[44:45], v[56:57] op_sel_hi:[1,0]
	v_mul_f32_e32 v66, 0xbfb8aa3b, v39
	v_mul_f32_e32 v47, 0xbfb8aa3b, v59
	v_mul_f32_e32 v56, 0xbfb8aa3b, v41
	v_mul_f32_e32 v57, 0xbfb8aa3b, v49
	v_mul_f32_e32 v62, 0xbfb8aa3b, v43
	v_mul_f32_e32 v63, 0xbfb8aa3b, v51
	v_mul_f32_e32 v64, 0xbfb8aa3b, v37
	v_mul_f32_e32 v65, 0xbfb8aa3b, v45
	v_exp_f32_e32 v66, v66
	v_exp_f32_e32 v47, v47
	v_exp_f32_e32 v56, v56
	v_exp_f32_e32 v57, v57
	v_exp_f32_e32 v62, v62
	v_exp_f32_e32 v63, v63
	v_exp_f32_e32 v64, v64
	v_exp_f32_e32 v65, v65
	v_add_f32_e32 v66, 1.0, v66
	v_add_f32_e32 v47, 1.0, v47
	v_add_f32_e32 v56, 1.0, v56
	v_add_f32_e32 v57, 1.0, v57
	v_add_f32_e32 v62, 1.0, v62
	v_add_f32_e32 v63, 1.0, v63
	v_add_f32_e32 v64, 1.0, v64
	v_add_f32_e32 v65, 1.0, v65
	v_rcp_f32_e32 v66, v66
	v_rcp_f32_e32 v47, v47
	v_rcp_f32_e32 v56, v56
	v_rcp_f32_e32 v57, v57
	v_rcp_f32_e32 v62, v62
	v_rcp_f32_e32 v63, v63
	v_rcp_f32_e32 v64, v64
	v_rcp_f32_e32 v65, v65
	v_mul_f32_e32 v39, v39, v66
	v_mul_f32_e32 v47, v59, v47
	v_mul_f32_e32 v41, v41, v56
	v_mul_f32_e32 v49, v49, v57
	v_mul_f32_e32 v43, v43, v62
	v_mul_f32_e32 v51, v51, v63
	v_mul_f32_e32 v37, v37, v64
	v_mul_f32_e32 v45, v45, v65
	v_mul_f32_e32 v39, v38, v39
	v_mul_f32_e32 v47, v58, v47
	v_mul_f32_e32 v40, v40, v41
	v_mul_f32_e32 v41, v48, v49
	v_mul_f32_e32 v42, v42, v43
	v_mul_f32_e32 v43, v50, v51
	v_mul_f32_e32 v48, v36, v37
	v_mul_f32_e32 v44, v44, v45
	v_cvt_pk_bf16_f32 v36, v47, v40
	v_cvt_pk_bf16_f32 v37, v41, v42
	v_cvt_pk_bf16_f32 v38, v43, v48
	v_cvt_pk_bf16_f32 v39, v44, v39
	global_store_dwordx4 v[52:53], v[36:39], off
	v_mov_b32_e32 v45, v24
	v_mov_b32_e32 v24, v33
	v_mov_b32_e32 v33, v26
	v_mov_b32_e32 v26, v35
	v_mov_b32_e32 v35, v20
	v_mov_b32_e32 v44, v32
	v_mov_b32_e32 v32, v34
	v_mov_b32_e32 v34, v28
	v_mov_b32_e32 v28, v30
	v_add_u32_e32 v30, 0xb0, v132
	v_mov_b64_e32 v[36:37], v[158:159]
	v_mov_b64_e32 v[38:39], v[160:161]
	v_mov_b64_e32 v[40:41], v[162:163]
	v_mov_b64_e32 v[42:43], v[164:165]
	v_mov_b32_e32 v48, v36
	v_mov_b32_e32 v49, v40
	v_mov_b32_e32 v40, v37
	v_mov_b32_e32 v36, v38
	v_mov_b32_e32 v37, v42
	v_mov_b32_e32 v42, v39
	v_pk_add_f32 v[38:39], v[48:49], v[40:41]
	v_pk_add_f32 v[36:37], v[36:37], v[42:43]
	s_nop 0
	v_pk_add_f32 v[36:37], v[38:39], v[36:37]
	s_nop 0
	v_add_f32_e32 v20, 0, v36
	v_add_f32_e32 v36, v20, v37
	ds_bpermute_b32 v37, v126, v36
	v_mov_b32_e32 v20, v29
	v_mov_b32_e32 v29, v22
	v_mov_b32_e32 v22, v31
	v_ashrrev_i32_e32 v31, 31, v30
	s_waitcnt lgkmcnt(0)
	v_add_f32_e32 v38, v36, v37
	ds_bpermute_b32 v39, v1, v38
	v_mad_i64_i32 v[36:37], s[10:11], v46, s72, v[60:61]
	v_lshl_add_u64 v[36:37], v[36:37], 0, v[2:3]
	s_waitcnt lgkmcnt(0)
	v_add_f32_e32 v38, v38, v39
	v_fmamk_f32 v38, v38, 0x3a000000, v226
	v_rsq_f32_e32 v40, v38
	v_lshlrev_b64 v[38:39], 7, v[30:31]
	v_lshl_add_u64 v[38:39], v[204:205], 0, v[38:39]
	v_pk_mul_f32 v[22:23], v[22:23], v[40:41] op_sel_hi:[1,0]
	v_pk_mul_f32 v[42:43], v[44:45], v[40:41] op_sel_hi:[1,0]
	v_pk_mul_f32 v[24:25], v[24:25], v[40:41] op_sel_hi:[1,0]
	v_pk_mul_f32 v[32:33], v[32:33], v[40:41] op_sel_hi:[1,0]
	v_pk_mul_f32 v[26:27], v[26:27], v[40:41] op_sel_hi:[1,0]
	v_pk_mul_f32 v[34:35], v[34:35], v[40:41] op_sel_hi:[1,0]
	v_pk_mul_f32 v[20:21], v[20:21], v[40:41] op_sel_hi:[1,0]
	v_pk_mul_f32 v[28:29], v[28:29], v[40:41] op_sel_hi:[1,0]
	v_mul_f32_e32 v48, 0xbfb8aa3b, v23
	v_mul_f32_e32 v31, 0xbfb8aa3b, v43
	v_mul_f32_e32 v40, 0xbfb8aa3b, v25
	v_mul_f32_e32 v41, 0xbfb8aa3b, v33
	v_mul_f32_e32 v44, 0xbfb8aa3b, v27
	v_mul_f32_e32 v45, 0xbfb8aa3b, v35
	v_mul_f32_e32 v46, 0xbfb8aa3b, v21
	v_mul_f32_e32 v47, 0xbfb8aa3b, v29
	v_exp_f32_e32 v48, v48
	v_exp_f32_e32 v31, v31
	v_exp_f32_e32 v40, v40
	v_exp_f32_e32 v41, v41
	v_exp_f32_e32 v44, v44
	v_exp_f32_e32 v45, v45
	v_exp_f32_e32 v46, v46
	v_exp_f32_e32 v47, v47
	v_add_f32_e32 v48, 1.0, v48
	v_add_f32_e32 v31, 1.0, v31
	v_add_f32_e32 v40, 1.0, v40
	v_add_f32_e32 v41, 1.0, v41
	v_add_f32_e32 v44, 1.0, v44
	v_add_f32_e32 v45, 1.0, v45
	v_add_f32_e32 v46, 1.0, v46
	v_add_f32_e32 v47, 1.0, v47
	v_rcp_f32_e32 v48, v48
	v_rcp_f32_e32 v31, v31
	v_rcp_f32_e32 v40, v40
	v_rcp_f32_e32 v41, v41
	v_rcp_f32_e32 v44, v44
	v_rcp_f32_e32 v45, v45
	v_rcp_f32_e32 v46, v46
	v_rcp_f32_e32 v47, v47
	v_mul_f32_e32 v23, v23, v48
	v_mul_f32_e32 v31, v43, v31
	v_mul_f32_e32 v25, v25, v40
	v_mul_f32_e32 v33, v33, v41
	v_mul_f32_e32 v27, v27, v44
	v_mul_f32_e32 v35, v35, v45
	v_mul_f32_e32 v21, v21, v46
	v_mul_f32_e32 v29, v29, v47
	v_mul_f32_e32 v23, v22, v23
	v_mul_f32_e32 v31, v42, v31
	v_mul_f32_e32 v24, v24, v25
	v_mul_f32_e32 v25, v32, v33
	v_mul_f32_e32 v26, v26, v27
	v_mul_f32_e32 v27, v34, v35
	v_mul_f32_e32 v32, v20, v21
	v_mul_f32_e32 v28, v28, v29
	v_cvt_pk_bf16_f32 v20, v31, v24
	v_cvt_pk_bf16_f32 v21, v25, v26
	v_cvt_pk_bf16_f32 v22, v27, v32
	v_cvt_pk_bf16_f32 v23, v28, v23
	global_store_dwordx4 v[36:37], v[20:23], off
	v_mov_b32_e32 v28, v16
	v_mov_b32_e32 v29, v8
	v_mov_b32_e32 v8, v17
	v_mov_b64_e32 v[20:21], v[166:167]
	v_mov_b64_e32 v[22:23], v[168:169]
	v_mov_b64_e32 v[24:25], v[170:171]
	v_mov_b64_e32 v[26:27], v[172:173]
	v_mov_b32_e32 v16, v20
	v_mov_b32_e32 v17, v24
	v_mov_b32_e32 v24, v21
	v_mov_b32_e32 v20, v22
	v_mov_b32_e32 v21, v26
	v_mov_b32_e32 v26, v23
	v_pk_add_f32 v[16:17], v[16:17], v[24:25]
	v_pk_add_f32 v[20:21], v[20:21], v[26:27]
	s_nop 0
	v_pk_add_f32 v[16:17], v[16:17], v[20:21]
	s_nop 0
	v_add_f32_e32 v16, 0, v16
	v_add_f32_e32 v20, v16, v17
	ds_bpermute_b32 v21, v126, v20
	v_mov_b32_e32 v17, v10
	v_mov_b32_e32 v10, v19
	v_mov_b32_e32 v19, v4
	v_mov_b32_e32 v4, v13
	s_waitcnt lgkmcnt(0)
	v_add_f32_e32 v20, v20, v21
	ds_bpermute_b32 v1, v1, v20
	v_mov_b32_e32 v13, v6
	v_mov_b32_e32 v16, v18
	v_mov_b32_e32 v18, v12
	v_mov_b32_e32 v12, v14
	s_waitcnt lgkmcnt(0)
	v_add_f32_e32 v1, v20, v1
	v_fmamk_f32 v1, v1, 0x3a000000, v226
	v_rsq_f32_e32 v20, v1
	v_mov_b32_e32 v6, v15
	v_mad_i64_i32 v[14:15], s[10:11], v30, s72, v[60:61]
	v_pk_mul_f32 v[6:7], v[6:7], v[20:21] op_sel_hi:[1,0]
	v_pk_mul_f32 v[22:23], v[28:29], v[20:21] op_sel_hi:[1,0]
	v_pk_mul_f32 v[8:9], v[8:9], v[20:21] op_sel_hi:[1,0]
	v_pk_mul_f32 v[16:17], v[16:17], v[20:21] op_sel_hi:[1,0]
	v_pk_mul_f32 v[10:11], v[10:11], v[20:21] op_sel_hi:[1,0]
	v_pk_mul_f32 v[18:19], v[18:19], v[20:21] op_sel_hi:[1,0]
	v_pk_mul_f32 v[4:5], v[4:5], v[20:21] op_sel_hi:[1,0]
	v_pk_mul_f32 v[12:13], v[12:13], v[20:21] op_sel_hi:[1,0]
	v_mul_f32_e32 v28, 0xbfb8aa3b, v7
	v_mul_f32_e32 v1, 0xbfb8aa3b, v23
	v_mul_f32_e32 v20, 0xbfb8aa3b, v9
	v_mul_f32_e32 v21, 0xbfb8aa3b, v17
	v_mul_f32_e32 v24, 0xbfb8aa3b, v11
	v_mul_f32_e32 v25, 0xbfb8aa3b, v19
	v_mul_f32_e32 v26, 0xbfb8aa3b, v5
	v_mul_f32_e32 v27, 0xbfb8aa3b, v13
	v_exp_f32_e32 v28, v28
	v_exp_f32_e32 v1, v1
	v_exp_f32_e32 v20, v20
	v_exp_f32_e32 v21, v21
	v_exp_f32_e32 v24, v24
	v_exp_f32_e32 v25, v25
	v_exp_f32_e32 v26, v26
	v_exp_f32_e32 v27, v27
	v_add_f32_e32 v28, 1.0, v28
	v_add_f32_e32 v1, 1.0, v1
	v_add_f32_e32 v20, 1.0, v20
	v_add_f32_e32 v21, 1.0, v21
	v_add_f32_e32 v24, 1.0, v24
	v_add_f32_e32 v25, 1.0, v25
	v_add_f32_e32 v26, 1.0, v26
	v_add_f32_e32 v27, 1.0, v27
	v_rcp_f32_e32 v28, v28
	v_rcp_f32_e32 v1, v1
	v_rcp_f32_e32 v20, v20
	v_rcp_f32_e32 v21, v21
	v_rcp_f32_e32 v24, v24
	v_rcp_f32_e32 v25, v25
	v_rcp_f32_e32 v26, v26
	v_rcp_f32_e32 v27, v27
	v_mul_f32_e32 v7, v7, v28
	v_mul_f32_e32 v1, v23, v1
	v_mul_f32_e32 v9, v9, v20
	v_mul_f32_e32 v17, v17, v21
	v_mul_f32_e32 v11, v11, v24
	v_mul_f32_e32 v19, v19, v25
	v_mul_f32_e32 v5, v5, v26
	v_mul_f32_e32 v13, v13, v27
	v_mul_f32_e32 v7, v6, v7
	v_lshl_add_u64 v[2:3], v[14:15], 0, v[2:3]
	v_mul_f32_e32 v1, v22, v1
	v_mul_f32_e32 v8, v8, v9
	v_mul_f32_e32 v9, v16, v17
	v_mul_f32_e32 v10, v10, v11
	v_mul_f32_e32 v11, v18, v19
	v_mul_f32_e32 v16, v4, v5
	v_mul_f32_e32 v12, v12, v13
	v_cvt_pk_bf16_f32 v4, v1, v8
	v_cvt_pk_bf16_f32 v5, v9, v10
	v_cvt_pk_bf16_f32 v6, v11, v16
	v_cvt_pk_bf16_f32 v7, v12, v7
	global_store_dwordx4 v[2:3], v[4:7], off
	s_andn2_b64 vcc, exec, s[26:27]
	s_mov_b64 s[10:11], -1
	s_cbranch_vccnz .LBB0_422
